# ple tiles: L2 warm-up touches for the K=256 f32 A rows issued with the tile prologue loads (k-loop prefetch distance is short), on top of v_ladder
# speedup vs baseline: 1.0068x; 1.0068x over previous
.LBB0_633:
	s_ashr_i32 s0, s28, 3
	s_lshr_b32 s1, s0, 29
	s_add_i32 s1, s0, s1
	s_and_b32 s16, s1, 0x1fffff8
	s_sub_i32 s0, s0, s16
	s_lshl_b32 s1, s1, 7
	s_lshl_b32 s16, s28, 7
	s_and_b32 s1, s1, 0xfffffc00
	s_and_b32 s16, s16, 0x380
	s_or_b32 s22, s1, s16
	s_ashr_i32 s23, s22, 31
	v_readlane_b32 s36, v254, 6
	s_lshl_b32 s0, s0, 7
	s_lshl_b64 s[30:31], s[22:23], 10
	v_readlane_b32 s38, v254, 8
	v_readlane_b32 s39, v254, 9
	s_add_u32 s30, s38, s30
	s_addc_u32 s31, s39, s31
	s_ashr_i32 s1, s0, 31
	v_mov_b32_e32 v26, v220
	s_lshl_b64 s[34:35], s[0:1], 9
	s_add_u32 s34, s3, s34
	v_ashrrev_i32_e32 v32, 2, v26
	v_add_u32_e32 v24, 64, v32
	v_ashrrev_i32_e32 v33, 31, v32
	v_lshlrev_b32_e32 v2, 3, v26
	s_addc_u32 s35, s4, s35
	v_lshlrev_b64 v[0:1], 9, v[32:33]
	v_and_b32_e32 v6, 24, v2
	v_ashrrev_i32_e32 v25, 31, v24
	v_min_i32_e32 v4, 0x7f, v32
	v_lshlrev_b64 v[2:3], 9, v[24:25]
	v_lshl_add_u64 v[0:1], s[34:35], 0, v[0:1]
	v_lshlrev_b32_e32 v176, 1, v6
	v_ashrrev_i32_e32 v5, 31, v4
	v_lshl_add_u64 v[2:3], s[34:35], 0, v[2:3]
	v_lshl_add_u64 v[34:35], v[0:1], 0, v[176:177]
	v_lshlrev_b64 v[0:1], 10, v[4:5]
	v_lshl_add_u64 v[40:41], v[2:3], 0, v[176:177]
	v_lshl_add_u64 v[0:1], s[30:31], 0, v[0:1]
	v_lshlrev_b32_e32 v176, 2, v6
	v_lshl_add_u64 v[42:43], v[0:1], 0, v[176:177]
	global_load_dwordx4 v[0:3], v[42:43], off nt
	global_load_dwordx4 v[4:7], v[42:43], off offset:16 nt
	v_min_i32_e32 v8, 0x7f, v24
	v_ashrrev_i32_e32 v9, 31, v8
	v_lshlrev_b64 v[8:9], 10, v[8:9]
	v_lshl_add_u64 v[8:9], s[30:31], 0, v[8:9]
	v_lshl_add_u64 v[48:49], v[8:9], 0, v[176:177]
	global_load_dwordx4 v[8:11], v[48:49], off nt
	global_load_dwordx4 v[12:15], v[48:49], off offset:16 nt
	global_load_dwordx4 v[16:19], v[34:35], off
	global_load_dwordx4 v[20:23], v[40:41], off
	v_lshlrev_b32_e32 v230, 2, v176
	v_mov_b32_e32 v231, 0
	v_lshl_add_u64 v[232:233], v[42:43], 0, v[230:231]
	v_lshl_add_u64 v[234:235], v[48:49], 0, v[230:231]
	global_load_dword v236, v[232:233], off
	global_load_dword v236, v[232:233], off offset:512
	global_load_dword v237, v[234:235], off
	global_load_dword v237, v[234:235], off offset:512
	v_lshrrev_b32_e32 v25, 4, v26
	v_lshrrev_b32_e32 v27, 2, v26
	v_sub_u32_e32 v29, 0, v25
	v_sub_u32_e32 v27, 0, v27
	v_xor_b32_e32 v29, v26, v29
	v_xor_b32_e32 v25, v25, v27
	v_lshlrev_b32_e32 v27, 4, v29
	v_and_b32_e32 v33, 48, v27
	v_lshl_or_b32 v27, v32, 6, v33
	v_and_b32_e32 v28, 15, v26
	v_lshl_or_b32 v24, v24, 6, v33
	v_and_b32_e32 v56, 0x4f, v26
	s_mov_b32 s29, 32
	s_mov_b32 s30, s17
	v_mov_b32_e32 v53, v177
	v_mov_b32_e32 v54, v177
	v_mov_b32_e32 v55, v177
	v_mov_b32_e32 v60, 0
	v_mov_b32_e32 v61, v177
	v_mov_b32_e32 v62, v177
	v_mov_b32_e32 v63, v177
	v_mov_b32_e32 v72, 0
	v_mov_b32_e32 v73, v177
	v_mov_b32_e32 v74, v177
	v_mov_b32_e32 v75, v177
	v_mov_b32_e32 v76, 0
	v_mov_b32_e32 v77, v177
	v_mov_b32_e32 v78, v177
	v_mov_b32_e32 v79, v177
	v_mov_b32_e32 v80, 0
	v_mov_b32_e32 v81, v177
	v_mov_b32_e32 v82, v177
	v_mov_b32_e32 v83, v177
	v_mov_b32_e32 v84, 0
	v_mov_b32_e32 v85, v177
	v_mov_b32_e32 v86, v177
	v_mov_b32_e32 v87, v177
	v_readlane_b32 s37, v254, 7
	v_readlane_b32 s40, v254, 10
	v_readlane_b32 s41, v254, 11
	v_readlane_b32 s42, v254, 12
	v_readlane_b32 s43, v254, 13
	v_readlane_b32 s44, v254, 14
	v_readlane_b32 s45, v254, 15
	v_readlane_b32 s46, v254, 16
	v_readlane_b32 s47, v254, 17
	v_readlane_b32 s48, v254, 18
	v_readlane_b32 s49, v254, 19
	v_readlane_b32 s50, v254, 20
	v_readlane_b32 s51, v254, 21
	s_waitcnt vmcnt(9)
	v_and_b32_sdwa v31, v3, v199 dst_sel:DWORD dst_unused:UNUSED_PAD src0_sel:WORD_1 src1_sel:DWORD
	v_and_b32_sdwa v36, v1, v199 dst_sel:DWORD dst_unused:UNUSED_PAD src0_sel:WORD_1 src1_sel:DWORD
	s_waitcnt vmcnt(8)
	v_and_b32_sdwa v39, v7, v199 dst_sel:DWORD dst_unused:UNUSED_PAD src0_sel:WORD_1 src1_sel:DWORD
	v_and_b32_sdwa v44, v5, v199 dst_sel:DWORD dst_unused:UNUSED_PAD src0_sel:WORD_1 src1_sel:DWORD
	v_and_b32_sdwa v29, v2, v199 dst_sel:DWORD dst_unused:UNUSED_PAD src0_sel:WORD_1 src1_sel:DWORD
	v_and_b32_sdwa v30, v0, v199 dst_sel:DWORD dst_unused:UNUSED_PAD src0_sel:WORD_1 src1_sel:DWORD
	v_and_b32_sdwa v37, v6, v199 dst_sel:DWORD dst_unused:UNUSED_PAD src0_sel:WORD_1 src1_sel:DWORD
	v_and_b32_sdwa v38, v4, v199 dst_sel:DWORD dst_unused:UNUSED_PAD src0_sel:WORD_1 src1_sel:DWORD
	v_add3_u32 v3, v3, v31, s9
	v_add3_u32 v1, v1, v36, s9
	v_add3_u32 v7, v7, v39, s9
	v_add3_u32 v5, v5, v44, s9
	v_add3_u32 v0, v0, v30, s9
	v_add3_u32 v2, v2, v29, s9
	v_add3_u32 v4, v4, v38, s9
	v_add3_u32 v6, v6, v37, s9
	v_and_b32_e32 v3, 0xffff0000, v3
	v_and_b32_e32 v29, 0xffff0000, v1
	v_and_b32_e32 v7, 0xffff0000, v7
	v_and_b32_e32 v5, 0xffff0000, v5
	v_or_b32_sdwa v1, v3, v2 dst_sel:DWORD dst_unused:UNUSED_PAD src0_sel:DWORD src1_sel:WORD_1
	v_or_b32_sdwa v0, v29, v0 dst_sel:DWORD dst_unused:UNUSED_PAD src0_sel:DWORD src1_sel:WORD_1
	v_or_b32_sdwa v3, v7, v6 dst_sel:DWORD dst_unused:UNUSED_PAD src0_sel:DWORD src1_sel:WORD_1
	v_or_b32_sdwa v2, v5, v4 dst_sel:DWORD dst_unused:UNUSED_PAD src0_sel:DWORD src1_sel:WORD_1
	ds_write_b128 v27, v[0:3]
	s_waitcnt vmcnt(6)
	v_and_b32_sdwa v3, v13, v199 dst_sel:DWORD dst_unused:UNUSED_PAD src0_sel:WORD_1 src1_sel:DWORD
	v_and_b32_sdwa v47, v11, v199 dst_sel:DWORD dst_unused:UNUSED_PAD src0_sel:WORD_1 src1_sel:DWORD
	v_and_b32_sdwa v50, v9, v199 dst_sel:DWORD dst_unused:UNUSED_PAD src0_sel:WORD_1 src1_sel:DWORD
	v_and_b32_sdwa v52, v12, v199 dst_sel:DWORD dst_unused:UNUSED_PAD src0_sel:WORD_1 src1_sel:DWORD
	v_and_b32_sdwa v2, v15, v199 dst_sel:DWORD dst_unused:UNUSED_PAD src0_sel:WORD_1 src1_sel:DWORD
	v_add3_u32 v3, v13, v3, s9
	v_and_b32_sdwa v45, v10, v199 dst_sel:DWORD dst_unused:UNUSED_PAD src0_sel:WORD_1 src1_sel:DWORD
	v_and_b32_sdwa v46, v8, v199 dst_sel:DWORD dst_unused:UNUSED_PAD src0_sel:WORD_1 src1_sel:DWORD
	v_and_b32_sdwa v51, v14, v199 dst_sel:DWORD dst_unused:UNUSED_PAD src0_sel:WORD_1 src1_sel:DWORD
	v_add3_u32 v11, v11, v47, s9
	v_add3_u32 v9, v9, v50, s9
	v_add3_u32 v0, v12, v52, s9
	v_add3_u32 v2, v15, v2, s9
	v_and_b32_e32 v3, 0xffff0000, v3
	v_add3_u32 v8, v8, v46, s9
	v_add3_u32 v10, v10, v45, s9
	v_and_b32_e32 v11, 0xffff0000, v11
	v_and_b32_e32 v9, 0xffff0000, v9
	v_add3_u32 v1, v14, v51, s9
	v_and_b32_e32 v2, 0xffff0000, v2
	v_or_b32_sdwa v6, v3, v0 dst_sel:DWORD dst_unused:UNUSED_PAD src0_sel:DWORD src1_sel:WORD_1
	v_ashrrev_i32_e32 v0, 1, v26
	v_or_b32_sdwa v5, v11, v10 dst_sel:DWORD dst_unused:UNUSED_PAD src0_sel:DWORD src1_sel:WORD_1
	v_or_b32_sdwa v4, v9, v8 dst_sel:DWORD dst_unused:UNUSED_PAD src0_sel:DWORD src1_sel:WORD_1
	v_or_b32_sdwa v7, v2, v1 dst_sel:DWORD dst_unused:UNUSED_PAD src0_sel:DWORD src1_sel:WORD_1
	v_and_or_b32 v50, v0, s24, v28
	v_lshlrev_b32_e32 v0, 4, v25
	ds_write_b128 v24, v[4:7]
	s_waitcnt vmcnt(5)
	ds_write_b128 v27, v[16:19] offset:16384
	s_waitcnt vmcnt(4)
	ds_write_b128 v24, v[20:23] offset:16384
	v_and_b32_e32 v51, 48, v0
	v_mov_b32_e32 v0, 0
	v_mov_b32_e32 v1, v177
	v_mov_b32_e32 v2, v177
	v_mov_b32_e32 v3, v177
	v_mov_b32_e32 v4, 0
	v_mov_b32_e32 v5, v177
	v_mov_b32_e32 v6, v177
	v_mov_b32_e32 v7, v177
	v_mov_b32_e32 v8, 0
	v_mov_b32_e32 v9, v177
	v_mov_b32_e32 v10, v177
	v_mov_b32_e32 v11, v177
	v_mov_b32_e32 v12, 0
	v_mov_b32_e32 v13, v177
	v_mov_b32_e32 v14, v177
	v_mov_b32_e32 v15, v177
	v_mov_b32_e32 v16, 0
	v_mov_b32_e32 v17, v177
	v_mov_b32_e32 v18, v177
	v_mov_b32_e32 v19, v177
	v_mov_b32_e32 v20, 0
	v_mov_b32_e32 v21, v177
	v_mov_b32_e32 v22, v177
	v_mov_b32_e32 v23, v177
	v_mov_b32_e32 v24, 0
	v_mov_b32_e32 v25, v177
	v_mov_b32_e32 v26, v177
	v_mov_b32_e32 v27, v177
	v_mov_b32_e32 v28, 0
	v_mov_b32_e32 v29, v177
	v_mov_b32_e32 v30, v177
	v_mov_b32_e32 v31, v177
	v_mov_b32_e32 v36, 0
	v_mov_b32_e32 v37, v177
	v_mov_b32_e32 v38, v177
	v_mov_b32_e32 v39, v177
	v_mov_b32_e32 v44, 0
	v_mov_b32_e32 v45, v177
	v_mov_b32_e32 v46, v177
	v_mov_b32_e32 v47, v177
	v_mov_b32_e32 v52, 0
	s_waitcnt lgkmcnt(0)
	s_barrier

.LBB0_1866:
	s_ashr_i32 s6, s21, 3
	s_lshr_b32 s8, s6, 29
	s_add_i32 s8, s6, s8
	s_and_b32 s9, s8, 0x1fffff8
	s_sub_i32 s6, s6, s9
	s_lshl_b32 s8, s8, 7
	s_lshl_b32 s9, s21, 7
	s_and_b32 s8, s8, 0xfffffc00
	s_and_b32 s9, s9, 0x380
	s_or_b32 s10, s8, s9
	s_ashr_i32 s11, s10, 31
	s_lshl_b32 s8, s6, 7
	s_lshl_b64 s[22:23], s[10:11], 10
	s_add_u32 s22, s3, s22
	s_addc_u32 s23, s4, s23
	s_ashr_i32 s9, s8, 31
	v_mov_b32_e32 v26, v220
	s_lshl_b64 s[24:25], s[8:9], 9
	s_add_u32 s24, s5, s24
	v_ashrrev_i32_e32 v64, 2, v26
	v_add_u32_e32 v24, 64, v64
	v_ashrrev_i32_e32 v65, 31, v64
	v_lshlrev_b32_e32 v2, 3, v26
	s_addc_u32 s25, s12, s25
	v_lshlrev_b64 v[0:1], 9, v[64:65]
	v_and_b32_e32 v6, 24, v2
	v_ashrrev_i32_e32 v25, 31, v24
	v_min_i32_e32 v4, 0x7f, v64
	v_lshlrev_b64 v[2:3], 9, v[24:25]
	v_lshl_add_u64 v[0:1], s[24:25], 0, v[0:1]
	v_lshlrev_b32_e32 v144, 1, v6
	v_ashrrev_i32_e32 v5, 31, v4
	v_lshl_add_u64 v[2:3], s[24:25], 0, v[2:3]
	v_lshl_add_u64 v[66:67], v[0:1], 0, v[144:145]
	v_lshlrev_b64 v[0:1], 10, v[4:5]
	v_lshl_add_u64 v[68:69], v[2:3], 0, v[144:145]
	v_lshl_add_u64 v[0:1], s[22:23], 0, v[0:1]
	v_lshlrev_b32_e32 v144, 2, v6
	v_lshl_add_u64 v[70:71], v[0:1], 0, v[144:145]
	global_load_dwordx4 v[0:3], v[70:71], off nt
	global_load_dwordx4 v[4:7], v[70:71], off offset:16 nt
	v_min_i32_e32 v8, 0x7f, v24
	v_ashrrev_i32_e32 v9, 31, v8
	v_lshlrev_b64 v[8:9], 10, v[8:9]
	v_lshl_add_u64 v[8:9], s[22:23], 0, v[8:9]
	v_lshl_add_u64 v[72:73], v[8:9], 0, v[144:145]
	global_load_dwordx4 v[8:11], v[72:73], off nt
	global_load_dwordx4 v[12:15], v[72:73], off offset:16 nt
	global_load_dwordx4 v[16:19], v[66:67], off
	global_load_dwordx4 v[20:23], v[68:69], off
	v_lshlrev_b32_e32 v230, 2, v144
	v_mov_b32_e32 v231, 0
	v_lshl_add_u64 v[232:233], v[70:71], 0, v[230:231]
	v_lshl_add_u64 v[234:235], v[72:73], 0, v[230:231]
	global_load_dword v236, v[232:233], off
	global_load_dword v236, v[232:233], off offset:512
	global_load_dword v237, v[234:235], off
	global_load_dword v237, v[234:235], off offset:512
	v_lshrrev_b32_e32 v25, 4, v26
	v_lshrrev_b32_e32 v27, 2, v26
	v_sub_u32_e32 v29, 0, v25
	v_sub_u32_e32 v27, 0, v27
	v_xor_b32_e32 v29, v26, v29
	v_xor_b32_e32 v25, v25, v27
	v_lshlrev_b32_e32 v27, 4, v29
	v_and_b32_e32 v65, 48, v27
	v_lshl_or_b32 v27, v64, 6, v65
	v_and_b32_e32 v28, 15, v26
	v_lshl_or_b32 v24, v24, 6, v65
	v_and_b32_e32 v76, 0x4f, v26
	s_mov_b32 s22, 32
	s_mov_b32 s23, s7
	v_mov_b32_e32 v56, 0
	v_mov_b32_e32 v57, v145
	v_mov_b32_e32 v58, v145
	v_mov_b32_e32 v59, v145
	v_mov_b32_e32 v60, 0
	v_mov_b32_e32 v61, v145
	v_mov_b32_e32 v62, v145
	v_mov_b32_e32 v63, v145
	v_mov_b32_e32 v44, 0
	v_mov_b32_e32 v45, v145
	v_mov_b32_e32 v46, v145
	v_mov_b32_e32 v47, v145
	v_mov_b32_e32 v43, v145
	v_mov_b32_e32 v48, 0
	v_mov_b32_e32 v49, v145
	v_mov_b32_e32 v50, v145
	v_mov_b32_e32 v51, v145
	v_mov_b32_e32 v52, 0
	v_mov_b32_e32 v53, v145
	v_mov_b32_e32 v54, v145
	v_mov_b32_e32 v55, v145
	s_waitcnt vmcnt(9)
	v_and_b32_sdwa v31, v3, v155 dst_sel:DWORD dst_unused:UNUSED_PAD src0_sel:WORD_1 src1_sel:DWORD
	v_and_b32_sdwa v32, v1, v155 dst_sel:DWORD dst_unused:UNUSED_PAD src0_sel:WORD_1 src1_sel:DWORD
	s_waitcnt vmcnt(8)
	v_and_b32_sdwa v35, v7, v155 dst_sel:DWORD dst_unused:UNUSED_PAD src0_sel:WORD_1 src1_sel:DWORD
	v_and_b32_sdwa v36, v5, v155 dst_sel:DWORD dst_unused:UNUSED_PAD src0_sel:WORD_1 src1_sel:DWORD
	v_and_b32_sdwa v29, v2, v155 dst_sel:DWORD dst_unused:UNUSED_PAD src0_sel:WORD_1 src1_sel:DWORD
	v_and_b32_sdwa v30, v0, v155 dst_sel:DWORD dst_unused:UNUSED_PAD src0_sel:WORD_1 src1_sel:DWORD
	v_and_b32_sdwa v33, v6, v155 dst_sel:DWORD dst_unused:UNUSED_PAD src0_sel:WORD_1 src1_sel:DWORD
	v_and_b32_sdwa v34, v4, v155 dst_sel:DWORD dst_unused:UNUSED_PAD src0_sel:WORD_1 src1_sel:DWORD
	v_add3_u32 v3, v3, v31, s17
	v_add3_u32 v1, v1, v32, s17
	v_add3_u32 v7, v7, v35, s17
	v_add3_u32 v5, v5, v36, s17
	v_add3_u32 v0, v0, v30, s17
	v_add3_u32 v2, v2, v29, s17
	v_add3_u32 v4, v4, v34, s17
	v_add3_u32 v6, v6, v33, s17
	v_and_b32_e32 v3, 0xffff0000, v3
	v_and_b32_e32 v29, 0xffff0000, v1
	v_and_b32_e32 v7, 0xffff0000, v7
	v_and_b32_e32 v5, 0xffff0000, v5
	v_or_b32_sdwa v1, v3, v2 dst_sel:DWORD dst_unused:UNUSED_PAD src0_sel:DWORD src1_sel:WORD_1
	v_or_b32_sdwa v0, v29, v0 dst_sel:DWORD dst_unused:UNUSED_PAD src0_sel:DWORD src1_sel:WORD_1
	v_or_b32_sdwa v3, v7, v6 dst_sel:DWORD dst_unused:UNUSED_PAD src0_sel:DWORD src1_sel:WORD_1
	v_or_b32_sdwa v2, v5, v4 dst_sel:DWORD dst_unused:UNUSED_PAD src0_sel:DWORD src1_sel:WORD_1
	ds_write_b128 v27, v[0:3]
	s_waitcnt vmcnt(6)
	v_and_b32_sdwa v3, v13, v155 dst_sel:DWORD dst_unused:UNUSED_PAD src0_sel:WORD_1 src1_sel:DWORD
	v_and_b32_sdwa v39, v11, v155 dst_sel:DWORD dst_unused:UNUSED_PAD src0_sel:WORD_1 src1_sel:DWORD
	v_and_b32_sdwa v40, v9, v155 dst_sel:DWORD dst_unused:UNUSED_PAD src0_sel:WORD_1 src1_sel:DWORD
	v_and_b32_sdwa v42, v12, v155 dst_sel:DWORD dst_unused:UNUSED_PAD src0_sel:WORD_1 src1_sel:DWORD
	v_and_b32_sdwa v2, v15, v155 dst_sel:DWORD dst_unused:UNUSED_PAD src0_sel:WORD_1 src1_sel:DWORD
	v_add3_u32 v3, v13, v3, s17
	v_and_b32_sdwa v37, v10, v155 dst_sel:DWORD dst_unused:UNUSED_PAD src0_sel:WORD_1 src1_sel:DWORD
	v_and_b32_sdwa v38, v8, v155 dst_sel:DWORD dst_unused:UNUSED_PAD src0_sel:WORD_1 src1_sel:DWORD
	v_and_b32_sdwa v41, v14, v155 dst_sel:DWORD dst_unused:UNUSED_PAD src0_sel:WORD_1 src1_sel:DWORD
	v_add3_u32 v11, v11, v39, s17
	v_add3_u32 v9, v9, v40, s17
	v_add3_u32 v0, v12, v42, s17
	v_add3_u32 v2, v15, v2, s17
	v_and_b32_e32 v3, 0xffff0000, v3
	v_add3_u32 v8, v8, v38, s17
	v_add3_u32 v10, v10, v37, s17
	v_and_b32_e32 v11, 0xffff0000, v11
	v_and_b32_e32 v9, 0xffff0000, v9
	v_add3_u32 v1, v14, v41, s17
	v_and_b32_e32 v2, 0xffff0000, v2
	v_or_b32_sdwa v6, v3, v0 dst_sel:DWORD dst_unused:UNUSED_PAD src0_sel:DWORD src1_sel:WORD_1
	v_ashrrev_i32_e32 v0, 1, v26
	v_or_b32_sdwa v5, v11, v10 dst_sel:DWORD dst_unused:UNUSED_PAD src0_sel:DWORD src1_sel:WORD_1
	v_or_b32_sdwa v4, v9, v8 dst_sel:DWORD dst_unused:UNUSED_PAD src0_sel:DWORD src1_sel:WORD_1
	v_or_b32_sdwa v7, v2, v1 dst_sel:DWORD dst_unused:UNUSED_PAD src0_sel:DWORD src1_sel:WORD_1
	v_and_or_b32 v74, v0, s18, v28
	v_lshlrev_b32_e32 v0, 4, v25
	ds_write_b128 v24, v[4:7]
	s_waitcnt vmcnt(5)
	ds_write_b128 v27, v[16:19] offset:16384
	s_waitcnt vmcnt(4)
	ds_write_b128 v24, v[20:23] offset:16384
	v_and_b32_e32 v75, 48, v0
	v_mov_b32_e32 v0, 0
	v_mov_b32_e32 v1, v145
	v_mov_b32_e32 v2, v145
	v_mov_b32_e32 v3, v145
	v_mov_b32_e32 v4, 0
	v_mov_b32_e32 v5, v145
	v_mov_b32_e32 v6, v145
	v_mov_b32_e32 v7, v145
	v_mov_b32_e32 v8, 0
	v_mov_b32_e32 v9, v145
	v_mov_b32_e32 v10, v145
	v_mov_b32_e32 v11, v145
	v_mov_b32_e32 v12, 0
	v_mov_b32_e32 v13, v145
	v_mov_b32_e32 v14, v145
	v_mov_b32_e32 v15, v145
	v_mov_b32_e32 v24, 0
	v_mov_b32_e32 v25, v145
	v_mov_b32_e32 v26, v145
	v_mov_b32_e32 v27, v145
	v_mov_b32_e32 v32, 0
	v_mov_b32_e32 v33, v145
	v_mov_b32_e32 v34, v145
	v_mov_b32_e32 v35, v145
	v_mov_b32_e32 v16, 0
	v_mov_b32_e32 v17, v145
	v_mov_b32_e32 v18, v145
	v_mov_b32_e32 v19, v145
	v_mov_b32_e32 v28, 0
	v_mov_b32_e32 v29, v145
	v_mov_b32_e32 v30, v145
	v_mov_b32_e32 v31, v145
	v_mov_b32_e32 v36, 0
	v_mov_b32_e32 v37, v145
	v_mov_b32_e32 v38, v145
	v_mov_b32_e32 v39, v145
	v_mov_b32_e32 v20, 0
	v_mov_b32_e32 v21, v145
	v_mov_b32_e32 v22, v145
	v_mov_b32_e32 v23, v145
	v_mov_b32_e32 v40, 0
	v_mov_b32_e32 v41, v145
	v_mov_b32_e32 v42, v145
	s_waitcnt lgkmcnt(0)
	s_barrier
